# weight conversion items beyond w_ada/w_qkv/w_o/w_sgu deferred to the idle workgroups of the adaLN GEMM phase
# speedup vs baseline: 1.0211x; 1.0211x over previous
.LBB0_635:
	s_andn2_b64 vcc, exec, s[2:3]
	s_cbranch_vccz .Lada_has_tile
	v_readlane_b32 s2, v253, 30
	s_add_i32 s3, s84, 0xffffffa0
	s_lshl_b32 s3, s3, 3
	s_add_i32 s3, s3, s2
	s_add_i32 s58, s3, 0x6800
	s_movk_i32 s40, 0xa0
	s_movk_i32 s70, 0x500
	s_mov_b32 s60, 0x93ff
	s_mov_b32 s61, 0x9400
	s_branch .Ldef_common
.Lada_has_tile:
	v_ashrrev_i32_e32 v0, 31, v14
	v_lshrrev_b32_e32 v0, 26, v0
	v_add_u32_e32 v0, v14, v0
	v_ashrrev_i32_e32 v15, 6, v0
	v_bfe_i32 v0, v14, 27, 1
	v_lshlrev_b32_e32 v3, 4, v14
	v_lshrrev_b32_e32 v0, 22, v0
	v_add_u32_e32 v0, v3, v0
	v_and_b32_e32 v0, 0xfffffc00, v0
	v_sub_u32_e32 v0, v3, v0
	v_lshrrev_b32_e32 v2, 4, v0
	v_bitop3_b32 v0, v2, v0, 32 bitop3:0x6c
	v_ashrrev_i32_e32 v5, 31, v0
	v_lshrrev_b32_e32 v5, 26, v5
	v_add_u32_e32 v5, v0, v5
	v_lshlrev_b32_e32 v2, 3, v15
	v_ashrrev_i32_e32 v16, 6, v5
	v_and_b32_e32 v5, 0xc0, v5
	v_and_b32_e32 v2, -16, v2
	v_sub_u32_e32 v0, v0, v5
	s_waitcnt lgkmcnt(0)
	v_mov_b32_e32 v8, 1
	v_add_u32_e32 v2, v16, v2
	v_ashrrev_i16_sdwa v0, v8, sext(v0) dst_sel:DWORD dst_unused:UNUSED_PAD src0_sel:DWORD src1_sel:BYTE_0
	v_lshlrev_b32_e32 v6, 5, v15
	v_bfe_i32 v17, v0, 0, 16
	v_lshlrev_b32_e32 v0, 1, v2
	v_lshrrev_b32_e32 v5, 2, v2
	v_and_b32_e32 v7, 3, v16
	s_mov_b32 s3, 0x1fffe0
	v_and_b32_e32 v6, 32, v6
	v_and_b32_e32 v0, 24, v0
	v_and_b32_e32 v5, 4, v5
	v_and_or_b32 v7, v2, s3, v7
	v_or3_b32 v0, v7, v5, v0
	v_add_lshl_u32 v5, v6, v17, 1
	v_add_u32_e32 v3, 0x2000, v3
	v_lshl_add_u32 v2, v2, 11, v5
	v_lshl_add_u32 v0, v0, 11, v5
	v_ashrrev_i32_e32 v5, 31, v3
	v_lshrrev_b32_e32 v5, 22, v5
	v_add_u32_e32 v5, v3, v5
	v_ashrrev_i32_e32 v18, 10, v5
	v_mul_i32_i24_e32 v5, 0x400, v18
	v_sub_u32_e32 v3, v3, v5
	v_lshrrev_b32_e32 v5, 4, v3
	v_bitop3_b32 v3, v5, v3, 32 bitop3:0x6c
	v_ashrrev_i32_e32 v6, 31, v3
	v_lshrrev_b32_e32 v6, 26, v6
	v_add_u32_e32 v6, v3, v6
	s_add_u32 s26, s82, 0x200000
	v_lshlrev_b32_e32 v5, 3, v18
	v_ashrrev_i32_e32 v19, 6, v6
	v_and_b32_e32 v6, 0xc0, v6
	s_addc_u32 s27, s83, 0
	v_and_b32_e32 v5, -16, v5
	v_sub_u32_e32 v3, v3, v6
	s_add_u32 s28, s82, 0xd200000
	v_add_u32_e32 v5, v19, v5
	v_ashrrev_i16_sdwa v3, v8, sext(v3) dst_sel:DWORD dst_unused:UNUSED_PAD src0_sel:DWORD src1_sel:BYTE_0
	v_and_b32_e32 v8, 3, v19
	s_addc_u32 s29, s83, 0
	v_and_or_b32 v8, v5, s3, v8
	s_ashr_i32 s3, s6, 6
	s_ashr_i32 s17, s16, 31
	s_ashr_i32 s19, s18, 31
	s_ashr_i32 s2, s6, 8
	s_lshl_b32 s30, s3, 10
	s_lshl_b64 s[4:5], s[16:17], 19
	s_lshl_b64 s[8:9], s[18:19], 19
	s_add_u32 s22, s28, s8
	v_lshlrev_b32_e32 v7, 5, v18
	v_bfe_i32 v20, v3, 0, 16
	v_lshlrev_b32_e32 v3, 1, v5
	v_lshrrev_b32_e32 v6, 2, v5
	s_addc_u32 s23, s29, s9
	s_add_i32 s19, s30, 0
	v_and_b32_e32 v7, 32, v7
	v_and_b32_e32 v3, 24, v3
	v_and_b32_e32 v6, 4, v6
	s_add_i32 m0, s19, 0x10000
	v_or3_b32 v3, v8, v6, v3
	v_add_lshl_u32 v6, v7, v20, 1
	global_load_lds_dwordx4 v0, s[22:23]
	s_add_i32 m0, s19, 0x12000
	v_lshl_add_u32 v152, v3, 11, v6
	s_add_u32 s8, s22, 0x40000
	global_load_lds_dwordx4 v152, s[22:23]
	s_addc_u32 s9, s23, 0
	s_add_i32 m0, s19, 0x14000
	v_lshl_add_u32 v150, v5, 11, v6
	global_load_lds_dwordx4 v0, s[8:9]
	s_add_i32 m0, s19, 0x16000
	s_add_u32 s20, s26, s4
	s_addc_u32 s21, s27, s5
	s_add_i32 s31, s19, 0x2000
	global_load_lds_dwordx4 v152, s[8:9]
	s_mov_b32 m0, s19
	s_add_u32 s4, s20, 0x40000
	global_load_lds_dwordx4 v2, s[20:21]
	s_mov_b32 m0, s31
	s_addc_u32 s5, s21, 0
	s_add_i32 s33, s19, 0x4000
	global_load_lds_dwordx4 v150, s[20:21]
	s_mov_b32 m0, s33
	s_add_i32 s34, s19, 0x6000
	global_load_lds_dwordx4 v2, s[4:5]
	s_mov_b32 m0, s34
	v_mov_b32_e32 v153, v1
	global_load_lds_dwordx4 v150, s[4:5]
	v_mov_b32_e32 v3, v1
	v_mov_b32_e32 v151, v1
	s_cmp_eq_u32 s2, 1
	v_lshl_add_u64 v[12:13], s[22:23], 0, v[0:1]
	v_lshl_add_u64 v[10:11], s[22:23], 0, v[152:153]
	v_lshl_add_u64 v[6:7], s[20:21], 0, v[2:3]
	s_cselect_b64 s[4:5], -1, 0
	s_cmp_lg_u32 s2, 1
	v_lshl_add_u64 v[8:9], s[20:21], 0, v[150:151]
	s_cbranch_scc1 .LBB0_638
	s_barrier

.LBB0_668:
	s_and_b64 vcc, exec, s[2:3]
	s_cbranch_vccz .LBB0_763
	s_mov_b32 s60, 0x67ff
	s_mov_b32 s61, 0x6800
.Ldef_common:
	s_cmp_gt_i32 s58, s60
	s_cbranch_scc1 .LBB0_728
	v_readlane_b32 s2, v253, 30
	s_lshl_b32 s2, s2, 14
	s_add_i32 s2, s2, 0
	s_lshl_b32 s14, s40, 4
	s_waitcnt lgkmcnt(0)
	s_add_u32 s15, s82, 0xd200000
	s_addc_u32 s16, s83, 0
	s_add_u32 s17, s82, 0x1000000
	s_addc_u32 s18, s83, 0
	s_add_u32 s19, s82, 0x1600000
	s_addc_u32 s20, s83, 0
	s_add_u32 s21, s82, 0x1a00000
	s_addc_u32 s22, s83, 0
	s_add_u32 s23, s82, 0x2a00000
	s_addc_u32 s24, s83, 0
	v_lshlrev_b32_e32 v0, 2, v233
	v_lshlrev_b32_e32 v3, 3, v233
	s_add_u32 s25, s82, 0x3200000
	v_lshrrev_b32_e32 v2, 4, v233
	v_and_b32_e32 v0, 60, v0
	s_waitcnt vmcnt(0)
	v_and_b32_e32 v84, 24, v3
	s_addc_u32 s26, s83, 0
	v_lshl_add_u32 v5, v0, 2, s2
	v_mul_u32_u24_e32 v6, 0x104, v2
	v_mul_u32_u24_e32 v3, 0x104, v84
	v_lshrrev_b32_e32 v86, 2, v233
	v_and_b32_e32 v7, 60, v233
	s_add_u32 s27, s82, 0x5e00000
	v_or_b32_e32 v70, 4, v2
	v_or_b32_e32 v72, 8, v2
	v_or_b32_e32 v74, 12, v2
	v_or_b32_e32 v76, 16, v2
	v_or_b32_e32 v78, 20, v2
	v_or_b32_e32 v80, 24, v2
	v_or_b32_e32 v82, 28, v2
	v_add3_u32 v3, s2, v3, v7
	v_or_b32_e32 v88, 16, v86
	v_or_b32_e32 v90, 32, v86
	v_or_b32_e32 v92, 48, v86
	s_addc_u32 s28, s83, 0
	v_lshlrev_b32_e32 v94, 2, v0
	v_add_u32_e32 v5, v5, v6
	s_mov_b32 s29, s58
	s_branch .LBB0_672
.LBB0_671:
	s_add_i32 s29, s29, s14
	s_cmp_gt_i32 s29, s60
	s_cbranch_scc1 .LBB0_728

.LBB0_686:
	v_mad_i64_i32 v[38:39], s[10:11], s34, v2, 0
	v_mad_i64_i32 v[40:41], s[10:11], s34, v70, 0
	v_mad_i64_i32 v[46:47], s[10:11], s34, v72, 0
	v_mad_i64_i32 v[48:49], s[10:11], s34, v74, 0
	v_mad_i64_i32 v[54:55], s[10:11], s34, v76, 0
	v_mad_i64_i32 v[56:57], s[10:11], s34, v78, 0
	v_mad_i64_i32 v[62:63], s[10:11], s34, v80, 0
	v_mad_i64_i32 v[64:65], s[10:11], s34, v82, 0
	v_lshl_add_u64 v[38:39], v[38:39], 2, s[4:5]
	v_mov_b32_e32 v95, v1
	v_lshl_add_u64 v[40:41], v[40:41], 2, s[4:5]
	v_lshl_add_u64 v[46:47], v[46:47], 2, s[4:5]
	v_lshl_add_u64 v[48:49], v[48:49], 2, s[4:5]
	v_lshl_add_u64 v[54:55], v[54:55], 2, s[4:5]
	v_lshl_add_u64 v[56:57], v[56:57], 2, s[4:5]
	v_lshl_add_u64 v[62:63], v[62:63], 2, s[4:5]
	v_lshl_add_u64 v[64:65], v[64:65], 2, s[4:5]
	v_lshl_add_u64 v[38:39], v[38:39], 0, v[94:95]
	v_lshl_add_u64 v[40:41], v[40:41], 0, v[94:95]
	v_lshl_add_u64 v[46:47], v[46:47], 0, v[94:95]
	v_lshl_add_u64 v[48:49], v[48:49], 0, v[94:95]
	v_lshl_add_u64 v[54:55], v[54:55], 0, v[94:95]
	v_lshl_add_u64 v[56:57], v[56:57], 0, v[94:95]
	v_lshl_add_u64 v[62:63], v[62:63], 0, v[94:95]
	v_lshl_add_u64 v[64:65], v[64:65], 0, v[94:95]
	global_load_dwordx4 v[42:45], v[38:39], off
	s_nop 0
	global_load_dwordx4 v[38:41], v[40:41], off
	s_nop 0
	global_load_dwordx4 v[50:53], v[46:47], off
	s_nop 0
	global_load_dwordx4 v[46:49], v[48:49], off
	s_nop 0
	global_load_dwordx4 v[58:61], v[54:55], off
	s_nop 0
	global_load_dwordx4 v[54:57], v[56:57], off
	s_nop 0
	global_load_dwordx4 v[66:69], v[62:63], off
	s_nop 0
	global_load_dwordx4 v[62:65], v[64:65], off
	s_add_i32 s36, s70, s29
	s_cmp_lt_i32 s36, s61
	s_cselect_b64 s[10:11], -1, 0
	s_and_b64 vcc, exec, s[10:11]
	s_cbranch_vccz .LBB0_702
	s_cmpk_gt_u32 s36, 0x2fff
	s_mov_b64 s[12:13], -1
	s_cbranch_scc1 .LBB0_716
	s_andn2_b64 vcc, exec, s[12:13]
	s_cbranch_vccz .LBB0_717

.LBB0_728:
	s_cmp_eq_u32 s71, 1
	s_cbranch_scc1 .LBB0_763
	v_lshl_or_b32 v2, s58, 6, v233
	s_mov_b32 s3, 0x10040
	s_lshl_b32 s2, s40, 9
	v_cmp_gt_i32_e32 vcc, s3, v2
	v_and_b32_e32 v5, 7, v241
	s_and_saveexec_b64 s[4:5], vcc
	s_cbranch_execz .LBB0_731
	v_lshlrev_b32_e32 v0, 3, v5
	s_waitcnt lgkmcnt(0)
	global_load_dwordx2 v[6:7], v0, s[54:55] offset:232
	s_add_u32 s6, s82, 0x100000
	s_addc_u32 s7, s83, 0
	s_mov_b64 s[8:9], 0
	v_mov_b32_e32 v0, v2
	s_waitcnt vmcnt(0)
